# attention K/V staging loads: scalar base + 32-bit lane offset (no 64-bit VALU adds in the key loop)
# baseline (speedup 1.0000x reference)
.LBB0_1255:
	s_cmp_lt_i32 s84, 16
	s_cselect_b64 s[4:5], -1, 0
	s_and_b64 s[0:1], s[4:5], s[0:1]
	s_andn2_b64 vcc, exec, s[0:1]
	s_cbranch_vccnz .LBB0_1273
	v_mov_b32_e32 v2, v181
	s_cmpk_gt_i32 s2, 0x3ff
	s_cbranch_scc1 .LBB0_1273
	s_add_u32 s6, s34, 0x6000000
	s_addc_u32 s7, s35, 0
	s_add_u32 s3, s34, 0x2200000
	v_ashrrev_i32_e32 v0, 4, v2
	s_addc_u32 s14, s35, 0
	v_lshlrev_b32_e32 v182, 7, v0
	v_xor_b32_e32 v0, v0, v2
	s_add_u32 s15, s34, 0x2800000
	v_lshlrev_b32_e32 v0, 4, v0
	s_addc_u32 s16, s35, 0
	s_not_b32 s0, s2
	v_mov_b32_e32 v1, 0
	v_and_b32_e32 v0, 0xf0, v0
	s_add_i32 s17, s82, s0
	v_lshl_add_u64 v[4:5], s[34:35], 0, v[0:1]
	s_mov_b64 s[0:1], 0x900000
	v_lshl_add_u64 v[184:185], v[4:5], 0, s[0:1]
	s_mov_b32 s0, 0x2aaaaaab
	v_mul_hi_i32 v5, v2, s0
	v_add_u32_e32 v0, 0x200, v2
	s_waitcnt lgkmcnt(0)
	v_lshrrev_b32_e32 v6, 31, v5
	v_ashrrev_i32_e32 v5, 2, v5
	v_add_u32_e32 v16, v5, v6
	v_mul_hi_i32 v5, v0, s0
	v_add_u32_e32 v4, 0x400, v2
	v_lshrrev_b32_e32 v6, 31, v5
	v_ashrrev_i32_e32 v5, 2, v5
	v_add_u32_e32 v17, v5, v6
	v_mul_hi_i32 v5, v4, s0
	v_bfe_u32 v3, v2, 5, 1
	v_lshrrev_b32_e32 v6, 31, v5
	v_ashrrev_i32_e32 v5, 2, v5
	s_movk_i32 s10, 0xc0
	s_movk_i32 s9, 0xffe8
	v_add_u32_e32 v18, v5, v6
	v_mul_lo_u32 v5, v16, s10
	v_mad_u64_u32 v[6:7], s[0:1], v16, s9, v[2:3]
	v_lshl_add_u32 v186, v6, 3, v5
	v_mul_lo_u32 v5, v17, s10
	v_mad_u64_u32 v[8:9], s[0:1], v17, s9, v[0:1]
	v_ashrrev_i32_e32 v12, 3, v0
	v_lshlrev_b32_e32 v0, 3, v2
	v_lshl_add_u32 v188, v8, 3, v5
	v_mad_u64_u32 v[4:5], s[0:1], v18, s9, v[4:5]
	v_and_b32_e32 v14, 56, v0
	v_mbcnt_lo_u32_b32 v0, -1, 0
	s_movk_i32 s0, 0x190
	v_mbcnt_hi_u32_b32 v0, -1, v0
	v_mul_lo_u32 v9, v17, s0
	v_and_b32_e32 v17, 64, v0
	v_lshl_add_u32 v5, v6, 4, 0
	v_lshl_add_u32 v6, v8, 4, 0
	v_mul_lo_u32 v8, v16, s0
	v_xor_b32_e32 v16, 32, v0
	v_add_u32_e32 v17, 64, v17
	v_cmp_lt_i32_e32 vcc, v16, v17
	v_and_b32_e32 v214, 31, v2
	v_lshlrev_b32_e32 v216, 4, v2
	v_cndmask_b32_e32 v0, v0, v16, vcc
	s_add_i32 s18, 0, 0x12000
	v_mov_b32_e32 v20, 0xf0
	v_lshlrev_b32_e32 v180, 3, v3
	v_lshlrev_b32_e32 v218, 2, v0
	v_lshl_add_u32 v0, v214, 8, s18
	v_bitop3_b32 v21, v216, 16, v20 bitop3:0x6c
	v_add3_u32 v220, v0, v21, v180
	v_bitop3_b32 v21, v216, 32, v20 bitop3:0x6c
	v_bitop3_b32 v22, v216, 48, v20 bitop3:0x6c
	s_movk_i32 s1, 0x50
	v_add3_u32 v221, v0, v21, v180
	v_add3_u32 v222, v0, v22, v180
	v_bitop3_b32 v21, v216, 64, v20 bitop3:0x6c
	v_bitop3_b32 v22, v216, s1, v20 bitop3:0x6c
	s_movk_i32 s1, 0x60
	v_add3_u32 v223, v0, v21, v180
	v_bitop3_b32 v21, v216, s1, v20 bitop3:0x6c
	s_movk_i32 s1, 0x70
	v_add3_u32 v224, v0, v22, v180
	v_bitop3_b32 v22, v216, s1, v20 bitop3:0x6c
	s_movk_i32 s1, 0x80
	v_add3_u32 v225, v0, v21, v180
	v_bitop3_b32 v21, v216, s1, v20 bitop3:0x6c
	s_movk_i32 s1, 0x90
	v_add3_u32 v226, v0, v22, v180
	v_bitop3_b32 v22, v216, s1, v20 bitop3:0x6c
	s_movk_i32 s1, 0xa0
	v_ashrrev_i32_e32 v10, 3, v2
	v_add3_u32 v227, v0, v21, v180
	v_bitop3_b32 v21, v216, s1, v20 bitop3:0x6c
	s_movk_i32 s1, 0xb0
	v_ashrrev_i32_e32 v11, 31, v10
	v_add3_u32 v228, v0, v22, v180
	v_bitop3_b32 v22, v216, s1, v20 bitop3:0x6c
	s_movk_i32 s1, 0xd0
	s_movk_i32 s8, 0xf0
	v_lshlrev_b64 v[192:193], 13, v[10:11]
	v_ashrrev_i32_e32 v13, 31, v12
	v_mul_lo_u32 v11, v18, s0
	s_movk_i32 s0, 0x88
	v_add3_u32 v229, v0, v21, v180
	v_add3_u32 v230, v0, v22, v180
	v_bitop3_b32 v21, v216, s10, v20 bitop3:0x6c
	v_bitop3_b32 v22, v216, s1, v20 bitop3:0x6c
	s_movk_i32 s1, 0xe0
	v_ashrrev_i32_e32 v15, 6, v2
	v_lshlrev_b64 v[194:195], 13, v[12:13]
	v_mul_lo_u32 v10, v10, s0
	v_mul_lo_u32 v12, v12, s0
	s_movk_i32 s0, 0x2200
	v_bfe_u32 v2, v2, 4, 2
	v_and_b32_e32 v19, 0xf0, v216
	v_add3_u32 v231, v0, v21, v180
	v_bitop3_b32 v20, v216, s1, v20 bitop3:0x6c
	v_bitop3_b32 v21, v216, s8, v216 bitop3:0xc
	v_lshlrev_b32_e32 v215, 5, v15
	v_mul_lo_u32 v7, v18, s10
	v_lshl_add_u32 v13, v3, 4, 0
	v_mul_lo_u32 v15, v15, s0
	s_movk_i32 s0, 0x110
	v_mul_u32_u24_e32 v16, 0x110, v214
	v_add3_u32 v219, v0, v19, v180
	v_add3_u32 v232, v0, v22, v180
	v_add3_u32 v233, v0, v20, v180
	v_add3_u32 v234, v0, v21, v180
	v_lshl_or_b32 v0, v2, 12, v19
	v_lshl_add_u32 v190, v4, 3, v7
	v_lshl_add_u32 v4, v4, 4, 0
	v_lshl_add_u32 v7, v14, 1, 0
	v_lshlrev_b32_e32 v217, 2, v3
	v_sub_u32_e32 v3, v13, v180
	v_add3_u32 v16, 0, v15, v16
	v_add_u32_e32 v196, 0x1000, v182
	v_add_u32_e32 v198, 0x2000, v182
	v_add_u32_e32 v200, 0x3000, v182
	v_mul_u32_u24_e32 v17, 0x190, v214
	v_mul_u32_u24_e32 v18, 0x88, v214
	v_lshl_add_u64 v[202:203], s[34:35], 0, v[0:1]
	v_mad_u32_u24 v0, v2, s0, v15
	s_movk_i32 s0, 0x6400
	v_ashrrev_i32_e32 v187, 31, v186
	v_ashrrev_i32_e32 v189, 31, v188
	v_ashrrev_i32_e32 v191, 31, v190
	v_lshlrev_b32_e32 v186, 1, v186
	v_lshlrev_b32_e32 v188, 1, v188
	v_lshlrev_b32_e32 v190, 1, v190
	s_mov_b32 s9, 0
	v_ashrrev_i32_e32 v183, 31, v182
	v_ashrrev_i32_e32 v197, 31, v196
	v_ashrrev_i32_e32 v199, 31, v198
	v_ashrrev_i32_e32 v201, 31, v200
	v_add3_u32 v235, v0, v19, 0
	s_movk_i32 s19, 0x1800
	v_lshlrev_b32_e32 v204, 1, v14
	v_add_u32_e32 v236, v5, v8
	v_add_u32_e32 v237, v6, v9
	v_add_u32_e32 v238, v4, v11
	v_add3_u32 v239, v7, v10, s0
	v_add3_u32 v240, v7, v12, s0
	v_add_u32_e32 v241, v13, v17
	s_mov_b32 s22, 0xf149f2ca
	s_mov_b32 s23, 0x41000000
	v_add_u32_e32 v242, v3, v18
	v_add_u32_e32 v243, v16, v180
	s_mov_b32 s36, 0xc004000
	s_mov_b32 s37, 0xc008000
	s_mov_b32 s38, 0xc00c000
	v_mov_b32_e32 v244, 0xf149f2ca
	s_mov_b32 s0, s2
	s_mov_b32 s39, 0
	v_lshrrev_b32_e32 v245, 3, v181
	v_mul_u32_u24_e32 v245, 0x90, v245
	v_and_b32_e32 v246, 7, v181
	v_lshrrev_b32_e32 v247, 1, v246
	v_lshl_add_u32 v245, v247, 5, v245
	v_and_b32_e32 v246, 1, v246
	v_lshl_add_u32 v245, v246, 3, v245
	v_add_u32_e32 v245, 0x6400, v245
	v_add_u32_e32 v246, 0x2400, v245
	v_and_b32_e32 v247, 31, v181
	v_mul_u32_u24_e32 v247, 0x90, v247
	v_bfe_u32 v248, v181, 5, 1
	v_lshl_add_u32 v247, v248, 4, v247
	v_add_u32_e32 v247, 0x6400, v247
.LBB0_1258:
	s_bfe_u32 s41, s0, 0x20004
	s_and_b32 s40, s0, 15
	s_lshl_b32 s0, s0, 2
	s_and_b32 s0, s0, 0xffffff00
	v_subrev_u32_e32 v2, s0, v215
	v_add_u32_e32 v206, 0xf00, v2
	v_or_b32_e32 v208, v206, v214
	s_lshl_b32 s8, s41, 12
	v_ashrrev_i32_e32 v209, 31, v208
	v_lshl_add_u64 v[4:5], s[8:9], 0, v[208:209]
	v_mov_b64_e32 v[6:7], s[6:7]
	v_mad_u64_u32 v[6:7], s[10:11], v4, s19, v[6:7]
	v_mad_i32_i24 v7, v5, s19, v7
	s_mul_i32 s8, s40, 0x180
	v_lshl_add_u64 v[4:5], v[6:7], 0, s[8:9]
	v_lshlrev_b32_e32 v0, 1, v180
	v_lshl_add_u64 v[4:5], v[4:5], 0, v[0:1]
	global_load_dwordx4 v[112:115], v[4:5], off
	global_load_dwordx4 v[116:119], v[4:5], off offset:32
	global_load_dwordx4 v[120:123], v[4:5], off offset:64
	global_load_dwordx4 v[124:127], v[4:5], off offset:96
	global_load_dwordx4 v[128:131], v[4:5], off offset:128
	global_load_dwordx4 v[132:135], v[4:5], off offset:160
	global_load_dwordx4 v[136:139], v[4:5], off offset:192
	global_load_dwordx4 v[140:143], v[4:5], off offset:224
	global_load_dwordx4 v[144:147], v[4:5], off offset:256
	global_load_dwordx4 v[148:151], v[4:5], off offset:288
	global_load_dwordx4 v[152:155], v[4:5], off offset:320
	global_load_dwordx4 v[156:159], v[4:5], off offset:352
	s_lshl_b32 s8, s40, 15
	v_add_u32_e32 v0, s18, v216
	v_lshl_add_u64 v[4:5], v[184:185], 0, s[8:9]
	v_readfirstlane_b32 s1, v0
	v_add_u32_e32 v3, 0x2000, v0
	v_lshl_add_u64 v[6:7], v[182:183], 1, v[4:5]
	s_mov_b32 m0, s1
	v_readfirstlane_b32 s1, v3
	v_add_u32_e32 v3, 0x4000, v0
	global_load_lds_dwordx4 v[6:7], off
	v_lshl_add_u64 v[6:7], v[196:197], 1, v[4:5]
	s_mov_b32 m0, s1
	v_readfirstlane_b32 s1, v3
	v_add_u32_e32 v0, 0x6000, v0
	global_load_lds_dwordx4 v[6:7], off
	v_lshl_add_u64 v[6:7], v[198:199], 1, v[4:5]
	s_mov_b32 m0, s1
	v_readfirstlane_b32 s1, v0
	global_load_lds_dwordx4 v[6:7], off
	v_lshl_add_u64 v[4:5], v[200:201], 1, v[4:5]
	s_mov_b32 m0, s1
	s_cmpk_eq_i32 s0, 0x1000
	global_load_lds_dwordx4 v[4:5], off
	s_cbranch_scc1 .LBB0_1269
	s_sub_i32 s0, 0x1000, s0
	s_lshr_b32 s42, s0, 6
	s_mul_i32 s0, s41, 0x180000
	s_add_u32 s0, s3, s0
	s_addc_u32 s1, s14, 0
	s_lshl_b32 s8, s41, 20
	s_add_u32 s10, s15, s8
	s_addc_u32 s11, s16, 0
	v_lshl_add_u64 v[4:5], s[10:11], 0, v[192:193]
	v_lshl_add_u64 v[6:7], s[10:11], 0, v[194:195]
	v_mov_b32_e32 v205, v1
	v_lshl_add_u64 v[210:211], v[4:5], 0, v[204:205]
	v_lshl_add_u64 v[212:213], v[6:7], 0, v[204:205]
	global_load_dwordx4 v[164:167], v[212:213], off
	global_load_dwordx4 v[160:163], v[210:211], off
	global_load_dwordx4 v[176:179], v190, s[0:1]
	global_load_dwordx4 v[168:171], v188, s[0:1]
	global_load_dwordx4 v[172:175], v186, s[0:1]
	v_subrev_u32_e32 v210, s34, v210
	v_subrev_u32_e32 v212, s34, v212
	v_mov_b32_e32 v14, v1
	v_mov_b32_e32 v15, v1
	v_add_u32_e32 v207, 0xf1f, v2
	v_mov_b32_e32 v0, v1
	v_mov_b32_e32 v2, v1
	v_mov_b32_e32 v3, v1
	v_mov_b32_e32 v4, v1
	v_mov_b32_e32 v5, v1
	v_mov_b32_e32 v6, v1
	v_mov_b32_e32 v7, v1
	v_mov_b32_e32 v8, v1
	v_mov_b32_e32 v9, v1
	v_mov_b32_e32 v10, v1
	v_mov_b32_e32 v11, v1
	v_mov_b32_e32 v12, v1
	v_mov_b32_e32 v13, v1
	v_mov_b64_e32 v[78:79], v[14:15]
	v_mov_b64_e32 v[62:63], v[14:15]
	v_mov_b64_e32 v[46:47], v[14:15]
	v_mov_b64_e32 v[30:31], v[14:15]
	s_mov_b32 s43, 0
	v_mov_b32_e32 v209, 0xf149f2ca
	v_mov_b32_e32 v205, 0
	v_mov_b64_e32 v[76:77], v[12:13]
	v_mov_b64_e32 v[74:75], v[10:11]
	v_mov_b64_e32 v[72:73], v[8:9]
	v_mov_b64_e32 v[70:71], v[6:7]
	v_mov_b64_e32 v[68:69], v[4:5]
	v_mov_b64_e32 v[66:67], v[2:3]
	v_mov_b64_e32 v[64:65], v[0:1]
	v_mov_b64_e32 v[60:61], v[12:13]
	v_mov_b64_e32 v[58:59], v[10:11]
	v_mov_b64_e32 v[56:57], v[8:9]
	v_mov_b64_e32 v[54:55], v[6:7]
	v_mov_b64_e32 v[52:53], v[4:5]
	v_mov_b64_e32 v[50:51], v[2:3]
	v_mov_b64_e32 v[48:49], v[0:1]
	v_mov_b64_e32 v[44:45], v[12:13]
	v_mov_b64_e32 v[42:43], v[10:11]
	v_mov_b64_e32 v[40:41], v[8:9]
	v_mov_b64_e32 v[38:39], v[6:7]
	v_mov_b64_e32 v[36:37], v[4:5]
	v_mov_b64_e32 v[34:35], v[2:3]
	v_mov_b64_e32 v[32:33], v[0:1]
	v_mov_b64_e32 v[28:29], v[12:13]
	v_mov_b64_e32 v[26:27], v[10:11]
	v_mov_b64_e32 v[24:25], v[8:9]
	v_mov_b64_e32 v[22:23], v[6:7]
	v_mov_b64_e32 v[20:21], v[4:5]
	v_mov_b64_e32 v[18:19], v[2:3]
	v_mov_b64_e32 v[16:17], v[0:1]
	s_mov_b32 s44, 0
	s_waitcnt vmcnt(0) lgkmcnt(0)
	s_barrier
	ds_write_b128 v236, v[172:175]
	ds_write_b128 v237, v[168:171]
	ds_write_b128 v238, v[176:179]
	ds_write2_b64 v245, v[160:161], v[162:163] offset1:2
	ds_write2_b64 v246, v[164:165], v[166:167] offset1:2
	v_add_u32_e32 v236, 0x1a000, v236
	v_add_u32_e32 v237, 0x1a000, v237
	v_add_u32_e32 v238, 0x1a000, v238
	v_add_u32_e32 v245, 0x4800, v245
	v_add_u32_e32 v246, 0x4800, v246
	s_cmp_lt_u32 s42, 2
	s_cbranch_scc1 .Lattn_p1
	s_mov_b32 s8, 64
	s_mul_i32 s10, s8, 0x180
	s_mul_hi_u32 s11, s8, 0x180
	s_add_u32 s10, s0, s10
	s_addc_u32 s11, s1, s11
	global_load_dwordx4 v[172:175], v186, s[10:11]
	global_load_dwordx4 v[168:171], v188, s[10:11]
	global_load_dwordx4 v[176:179], v190, s[10:11]
	s_lshl_b32 s10, s8, 1
	s_add_u32 s10, s34, s10
	s_addc_u32 s11, s35, 0
	global_load_dwordx4 v[160:163], v210, s[10:11]
	global_load_dwordx4 v[164:167], v212, s[10:11]

.LBB0_1262:
	s_add_i32 s44, s44, 1
	s_cmp_ge_u32 s44, s42
	s_cbranch_scc1 .LBB0_1264
	s_waitcnt vmcnt(0)
	ds_write_b128 v236, v[172:175]
	ds_write_b128 v237, v[168:171]
	ds_write_b128 v238, v[176:179]
	ds_write2_b64 v245, v[160:161], v[162:163] offset1:2
	ds_write2_b64 v246, v[164:165], v[166:167] offset1:2
	s_add_i32 s8, s44, 1
	s_cmp_ge_u32 s8, s42
	s_cbranch_scc1 .LBB0_1264
	s_add_i32 s8, s43, 128
	s_mul_i32 s10, s8, 0x180
	s_mul_hi_u32 s11, s8, 0x180
	s_add_u32 s10, s0, s10
	s_addc_u32 s11, s1, s11
	global_load_dwordx4 v[172:175], v186, s[10:11]
	global_load_dwordx4 v[168:171], v188, s[10:11]
	global_load_dwordx4 v[176:179], v190, s[10:11]
	s_lshl_b32 s10, s8, 1
	s_add_u32 s10, s34, s10
	s_addc_u32 s11, s35, 0
	global_load_dwordx4 v[160:163], v210, s[10:11]
	global_load_dwordx4 v[164:167], v212, s[10:11]
